# c9 + P16 epilogue: second half-tile base loads issued together with the first half's (into free v220-251), vmcnt waits adjusted
# baseline (speedup 1.0000x reference)
; __device__ __forceinline__ unsigned cvt_pk_bf16(float lo, float hi) { unsigned r; asm volatile("v_cvt_pk_bf16_f32 %0, %1, %2" : "=v"(r) : "v"(lo), "v"(hi)); return r; }
;     __device__ __forceinline__ void operator()(const f32x4 (&acc)[2][2][4][2], const Unit& u, int wr, int wc, int fr, int fq) const {
;     ...
;             for (int m = 0; m < 4; ++m) { const size_t off = (size_t)(row0 + ai * HALF + m * 16) * 1024 + col0;
; #pragma unroll
;                 for (int bj = 0; bj < 2; ++bj)
; #pragma unroll
;                     for (int n = 0; n < 2; ++n) {
;                         if (BASE_BF16) bw[m][bj][n] = __builtin_nontemporal_load((const unsigned long long*)((const bf16_t*)base + off + bj * HALF + 16 * n));
;                         else bv[m][bj][n] = __builtin_nontemporal_load((const f32x4*)((const float*)base + off + bj * HALF + 16 * n)); } }
;             asm volatile("" ::: "memory");
; #pragma unroll
;             for (int m = 0; m < 4; ++m) { const size_t off = (size_t)(row0 + ai * HALF + m * 16) * 1024 + col0;
; #pragma unroll
;                 for (int bj = 0; bj < 2; ++bj)
; #pragma unroll
;                     for (int n = 0; n < 2; ++n) {
;                         f32x4 b4;
;                         if (BASE_BF16) { const unsigned long long w = bw[m][bj][n];
;                             b4 = (f32x4){__uint_as_float((unsigned)(w & 0xffffull) << 16), __uint_as_float((unsigned)((w >> 16) & 0xffffull) << 16),
;                                          __uint_as_float((unsigned)((w >> 32) & 0xffffull) << 16), __uint_as_float((unsigned)((w >> 48) & 0xffffull) << 16)}; }
;                         else b4 = bv[m][bj][n];
;                         const f32x4 o = b4 + gv[bj][n] * acc[ai][bj][m][n];
;                         if (OUT_BF16) *(unsigned long long*)((bf16_t*)out + off + bj * HALF + 16 * n) = (unsigned long long)cvt_pk_bf16(o[0], o[1]) | ((unsigned long long)cvt_pk_bf16(o[2], o[3]) << 32);
;                         else *(f32x4*)((float*)out + off + bj * HALF + 16 * n) = o; } }
.LBB0_1483:
	v_lshl_or_b32 v128, s28, 8, v166
	v_lshl_add_u32 v160, s3, 8, v164
	v_ashrrev_i32_e32 v129, 31, v128
	v_ashrrev_i32_e32 v161, 31, v160
	v_or_b32_e32 v178, 16, v160
	v_lshl_add_u64 v[158:159], v[128:129], 1, s[8:9]
	v_lshlrev_b64 v[130:131], 11, v[160:161]
	s_lshr_b32 s3, s3, 4
	v_ashrrev_i32_e32 v179, 31, v178
	v_lshl_add_u64 v[130:131], v[158:159], 0, v[130:131]
	s_mul_i32 s16, s3, 0x1800
	v_lshlrev_b64 v[156:157], 2, v[128:129]
	v_lshlrev_b64 v[128:129], 11, v[178:179]
	global_load_dwordx2 v[170:171], v[130:131], off nt
	global_load_dwordx2 v[172:173], v[130:131], off offset:32 nt
	global_load_dwordx2 v[174:175], v[130:131], off offset:256 nt
	global_load_dwordx2 v[176:177], v[130:131], off offset:288 nt
	s_ashr_i32 s17, s16, 31
	v_lshl_add_u64 v[162:163], v[158:159], 0, v[128:129]
	global_load_dwordx2 v[180:181], v[162:163], off nt
	s_lshl_b64 s[16:17], s[16:17], 2
	s_add_u32 s16, s41, s16
	s_addc_u32 s17, s42, s17
	v_lshl_add_u64 v[128:129], s[16:17], 0, v[156:157]
	global_load_dwordx4 v[140:143], v[128:129], off
	global_load_dwordx4 v[136:139], v[128:129], off offset:64
	global_load_dwordx4 v[132:135], v[128:129], off offset:512
	s_nop 0
	global_load_dwordx4 v[128:131], v[128:129], off offset:576
	s_nop 0
	global_load_dwordx2 v[182:183], v[162:163], off offset:32 nt
	global_load_dwordx2 v[184:185], v[162:163], off offset:256 nt
	global_load_dwordx2 v[186:187], v[162:163], off offset:288 nt
	v_or_b32_e32 v188, 32, v160
	v_ashrrev_i32_e32 v189, 31, v188
	v_lshlrev_b64 v[192:193], 11, v[188:189]
	v_lshl_add_u64 v[192:193], v[158:159], 0, v[192:193]
	global_load_dwordx2 v[196:197], v[192:193], off nt
	v_or_b32_e32 v162, 48, v160
	v_ashrrev_i32_e32 v163, 31, v162
	v_lshlrev_b64 v[194:195], 11, v[162:163]
	v_lshl_add_u64 v[194:195], v[158:159], 0, v[194:195]
	global_load_dwordx2 v[198:199], v[192:193], off offset:32 nt
	global_load_dwordx2 v[200:201], v[192:193], off offset:256 nt
	s_nop 0
	global_load_dwordx2 v[192:193], v[192:193], off offset:288 nt
	s_nop 0
	global_load_dwordx2 v[202:203], v[194:195], off nt
	global_load_dwordx2 v[204:205], v[194:195], off offset:32 nt
	global_load_dwordx2 v[206:207], v[194:195], off offset:256 nt
	s_nop 0
	global_load_dwordx2 v[194:195], v[194:195], off offset:288 nt
	v_lshlrev_b64 v[190:191], 12, v[160:161]
	v_lshl_add_u64 v[190:191], s[50:51], 0, v[190:191]
	v_lshlrev_b64 v[178:179], 12, v[178:179]
	v_lshl_add_u64 v[190:191], v[190:191], 0, v[156:157]
	v_add_u32_e32 v252, 0x80, v160
	v_ashrrev_i32_e32 v253, 31, v252
	v_lshlrev_b64 v[252:253], 11, v[252:253]
	v_lshl_add_u64 v[252:253], v[158:159], 0, v[252:253]
	global_load_dwordx2 v[220:221], v[252:253], off nt
	global_load_dwordx2 v[222:223], v[252:253], off offset:32 nt
	global_load_dwordx2 v[224:225], v[252:253], off offset:256 nt
	global_load_dwordx2 v[226:227], v[252:253], off offset:288 nt
	v_add_u32_e32 v252, 0x90, v160
	v_ashrrev_i32_e32 v253, 31, v252
	v_lshlrev_b64 v[252:253], 11, v[252:253]
	v_lshl_add_u64 v[252:253], v[158:159], 0, v[252:253]
	global_load_dwordx2 v[228:229], v[252:253], off nt
	global_load_dwordx2 v[230:231], v[252:253], off offset:32 nt
	global_load_dwordx2 v[232:233], v[252:253], off offset:256 nt
	global_load_dwordx2 v[234:235], v[252:253], off offset:288 nt
	v_add_u32_e32 v252, 0xa0, v160
	v_ashrrev_i32_e32 v253, 31, v252
	v_lshlrev_b64 v[252:253], 11, v[252:253]
	v_lshl_add_u64 v[252:253], v[158:159], 0, v[252:253]
	global_load_dwordx2 v[236:237], v[252:253], off nt
	global_load_dwordx2 v[238:239], v[252:253], off offset:32 nt
	global_load_dwordx2 v[240:241], v[252:253], off offset:256 nt
	global_load_dwordx2 v[242:243], v[252:253], off offset:288 nt
	v_add_u32_e32 v252, 0xb0, v160
	v_ashrrev_i32_e32 v253, 31, v252
	v_lshlrev_b64 v[252:253], 11, v[252:253]
	v_lshl_add_u64 v[252:253], v[158:159], 0, v[252:253]
	global_load_dwordx2 v[244:245], v[252:253], off nt
	global_load_dwordx2 v[246:247], v[252:253], off offset:32 nt
	global_load_dwordx2 v[250:251], v[252:253], off offset:256 nt
	global_load_dwordx2 v[248:249], v[252:253], off offset:288 nt
	s_and_b64 vcc, exec, s[0:1]
	s_mov_b64 s[0:1], -1
	s_waitcnt vmcnt(16)
	v_alignbit_b32 v161, v171, v170, 16
	v_lshlrev_b32_e32 v208, 16, v170
	v_and_b32_e32 v209, 0xffff0000, v170
	v_and_b32_e32 v171, 0xffff0000, v171
	v_lshlrev_b32_e32 v210, 16, v172
	v_and_b32_e32 v211, 0xffff0000, v172
	v_alignbit_b32 v172, v173, v172, 16
	v_lshlrev_b32_e32 v212, 16, v174
	v_and_b32_e32 v213, 0xffff0000, v174
	v_alignbit_b32 v174, v175, v174, 16
	v_lshlrev_b32_e32 v214, 16, v176
	v_and_b32_e32 v215, 0xffff0000, v176
	v_alignbit_b32 v176, v177, v176, 16
	v_and_b32_e32 v170, 0xffff0000, v161
	v_and_b32_e32 v173, 0xffff0000, v173
	v_and_b32_e32 v175, 0xffff0000, v175
	v_and_b32_e32 v177, 0xffff0000, v177
	v_and_b32_e32 v172, 0xffff0000, v172
	v_and_b32_e32 v174, 0xffff0000, v174
	v_and_b32_e32 v176, 0xffff0000, v176
	v_alignbit_b32 v161, v181, v180, 16
	v_pk_fma_f32 v[124:125], v[124:125], v[140:141], v[208:209]
	v_pk_fma_f32 v[126:127], v[126:127], v[142:143], v[170:171]
	v_pk_fma_f32 v[112:113], v[112:113], v[132:133], v[212:213]
	v_lshlrev_b32_e32 v216, 16, v180
	v_and_b32_e32 v217, 0xffff0000, v180
	v_and_b32_e32 v181, 0xffff0000, v181
	v_and_b32_e32 v180, 0xffff0000, v161
	v_pk_fma_f32 v[120:121], v[120:121], v[136:137], v[210:211]
	v_pk_fma_f32 v[122:123], v[122:123], v[138:139], v[172:173]
	v_pk_fma_f32 v[114:115], v[114:115], v[134:135], v[174:175]
	v_pk_fma_f32 v[108:109], v[108:109], v[128:129], v[214:215]
	v_pk_fma_f32 v[110:111], v[110:111], v[130:131], v[176:177]
	global_store_dwordx4 v[190:191], v[124:127], off
	global_store_dwordx4 v[190:191], v[120:123], off offset:64
; __device__ __forceinline__ unsigned cvt_pk_bf16(float lo, float hi) { unsigned r; asm volatile("v_cvt_pk_bf16_f32 %0, %1, %2" : "=v"(r) : "v"(lo), "v"(hi)); return r; }
;     __device__ __forceinline__ void operator()(const f32x4 (&acc)[2][2][4][2], const Unit& u, int wr, int wc, int fr, int fq) const {
;     ...
;             for (int m = 0; m < 4; ++m) { const size_t off = (size_t)(row0 + ai * HALF + m * 16) * 1024 + col0;
; #pragma unroll
;                 for (int bj = 0; bj < 2; ++bj)
; #pragma unroll
;                     for (int n = 0; n < 2; ++n) {
;                         f32x4 b4;
;                         if (BASE_BF16) { const unsigned long long w = bw[m][bj][n];
;                             b4 = (f32x4){__uint_as_float((unsigned)(w & 0xffffull) << 16), __uint_as_float((unsigned)((w >> 16) & 0xffffull) << 16),
;                                          __uint_as_float((unsigned)((w >> 32) & 0xffffull) << 16), __uint_as_float((unsigned)((w >> 48) & 0xffffull) << 16)}; }
;                         else b4 = bv[m][bj][n];
;                         const f32x4 o = b4 + gv[bj][n] * acc[ai][bj][m][n];
;                         if (OUT_BF16) *(unsigned long long*)((bf16_t*)out + off + bj * HALF + 16 * n) = (unsigned long long)cvt_pk_bf16(o[0], o[1]) | ((unsigned long long)cvt_pk_bf16(o[2], o[3]) << 32);
;                         else *(f32x4*)((float*)out + off + bj * HALF + 16 * n) = o; } }
	global_store_dwordx4 v[190:191], v[112:115], off offset:512
	global_store_dwordx4 v[190:191], v[108:111], off offset:576
	s_nop 0
	v_lshl_add_u64 v[112:113], s[50:51], 0, v[178:179]
	v_pk_fma_f32 v[108:109], v[116:117], v[140:141], v[216:217]
	v_pk_fma_f32 v[110:111], v[118:119], v[142:143], v[180:181]
	v_lshl_add_u64 v[112:113], v[112:113], 0, v[156:157]
	global_store_dwordx4 v[112:113], v[108:111], off
	s_nop 1
	v_alignbit_b32 v110, v183, v182, 16
	v_lshlrev_b32_e32 v108, 16, v182
	v_and_b32_e32 v109, 0xffff0000, v182
	v_and_b32_e32 v110, 0xffff0000, v110
	v_and_b32_e32 v111, 0xffff0000, v183
	v_pk_fma_f32 v[104:105], v[104:105], v[136:137], v[108:109]
	v_pk_fma_f32 v[106:107], v[106:107], v[138:139], v[110:111]
	global_store_dwordx4 v[112:113], v[104:107], off offset:64
	s_nop 1
	v_alignbit_b32 v106, v185, v184, 16
	v_lshlrev_b32_e32 v104, 16, v184
	v_and_b32_e32 v105, 0xffff0000, v184
	v_and_b32_e32 v106, 0xffff0000, v106
	v_and_b32_e32 v107, 0xffff0000, v185
	v_pk_fma_f32 v[100:101], v[100:101], v[132:133], v[104:105]
	v_pk_fma_f32 v[102:103], v[102:103], v[134:135], v[106:107]
	global_store_dwordx4 v[112:113], v[100:103], off offset:512
	s_nop 1
	v_alignbit_b32 v102, v187, v186, 16
	v_lshlrev_b32_e32 v100, 16, v186
	v_and_b32_e32 v101, 0xffff0000, v186
	v_and_b32_e32 v102, 0xffff0000, v102
	v_and_b32_e32 v103, 0xffff0000, v187
	v_pk_fma_f32 v[92:93], v[92:93], v[128:129], v[100:101]
	v_pk_fma_f32 v[94:95], v[94:95], v[130:131], v[102:103]
	global_store_dwordx4 v[112:113], v[92:95], off offset:576
	v_lshlrev_b64 v[100:101], 12, v[188:189]
	s_nop 0
	v_lshlrev_b32_e32 v92, 16, v196
	v_and_b32_e32 v93, 0xffff0000, v196
	v_alignbit_b32 v94, v197, v196, 16
	v_and_b32_e32 v94, 0xffff0000, v94
	v_and_b32_e32 v95, 0xffff0000, v197
	v_pk_fma_f32 v[92:93], v[96:97], v[140:141], v[92:93]
	v_lshl_add_u64 v[96:97], s[50:51], 0, v[100:101]
	v_pk_fma_f32 v[94:95], v[98:99], v[142:143], v[94:95]
	v_lshl_add_u64 v[96:97], v[96:97], 0, v[156:157]
	global_store_dwordx4 v[96:97], v[92:95], off
	v_add_u32_e32 v98, 0xb0, v160
	v_ashrrev_i32_e32 v99, 31, v98
	v_alignbit_b32 v94, v199, v198, 16
	v_lshlrev_b32_e32 v92, 16, v198
	v_and_b32_e32 v93, 0xffff0000, v198
	v_and_b32_e32 v94, 0xffff0000, v94
	v_and_b32_e32 v95, 0xffff0000, v199
	v_pk_fma_f32 v[88:89], v[88:89], v[136:137], v[92:93]
	v_pk_fma_f32 v[90:91], v[90:91], v[138:139], v[94:95]
	global_store_dwordx4 v[96:97], v[88:91], off offset:64
	s_nop 1
	v_alignbit_b32 v90, v201, v200, 16
	v_lshlrev_b32_e32 v88, 16, v200
	v_and_b32_e32 v89, 0xffff0000, v200
	v_and_b32_e32 v90, 0xffff0000, v90
	v_and_b32_e32 v91, 0xffff0000, v201
	v_pk_fma_f32 v[84:85], v[84:85], v[132:133], v[88:89]
	v_pk_fma_f32 v[86:87], v[86:87], v[134:135], v[90:91]
	global_store_dwordx4 v[96:97], v[84:87], off offset:512
	v_add_u32_e32 v88, 0xa0, v160
	v_ashrrev_i32_e32 v89, 31, v88
	v_alignbit_b32 v86, v193, v192, 16
	v_lshlrev_b32_e32 v84, 16, v192
	v_and_b32_e32 v85, 0xffff0000, v192
	v_and_b32_e32 v86, 0xffff0000, v86
	v_and_b32_e32 v87, 0xffff0000, v193
	v_pk_fma_f32 v[76:77], v[76:77], v[128:129], v[84:85]
	v_pk_fma_f32 v[78:79], v[78:79], v[130:131], v[86:87]
	global_store_dwordx4 v[96:97], v[76:79], off offset:576
	v_lshlrev_b64 v[84:85], 12, v[162:163]
	s_nop 0
	v_lshlrev_b32_e32 v76, 16, v202
	v_and_b32_e32 v77, 0xffff0000, v202
	v_alignbit_b32 v78, v203, v202, 16
	v_and_b32_e32 v78, 0xffff0000, v78
	v_and_b32_e32 v79, 0xffff0000, v203
	v_pk_fma_f32 v[76:77], v[80:81], v[140:141], v[76:77]
	v_lshl_add_u64 v[80:81], s[50:51], 0, v[84:85]
	v_pk_fma_f32 v[78:79], v[82:83], v[142:143], v[78:79]
	v_lshl_add_u64 v[80:81], v[80:81], 0, v[156:157]
	global_store_dwordx4 v[80:81], v[76:79], off
	s_nop 1
	v_alignbit_b32 v78, v205, v204, 16
	v_lshlrev_b32_e32 v76, 16, v204
	v_and_b32_e32 v77, 0xffff0000, v204
	v_and_b32_e32 v78, 0xffff0000, v78
	v_and_b32_e32 v79, 0xffff0000, v205
	v_pk_fma_f32 v[72:73], v[72:73], v[136:137], v[76:77]
	v_pk_fma_f32 v[74:75], v[74:75], v[138:139], v[78:79]
	global_store_dwordx4 v[80:81], v[72:75], off offset:64
	v_add_u32_e32 v78, 0x90, v160
	v_ashrrev_i32_e32 v79, 31, v78
	v_alignbit_b32 v74, v207, v206, 16
	v_lshlrev_b32_e32 v72, 16, v206
	v_and_b32_e32 v73, 0xffff0000, v206
	v_and_b32_e32 v74, 0xffff0000, v74
	v_and_b32_e32 v75, 0xffff0000, v207
	v_pk_fma_f32 v[68:69], v[68:69], v[132:133], v[72:73]
	v_pk_fma_f32 v[70:71], v[70:71], v[134:135], v[74:75]
	global_store_dwordx4 v[80:81], v[68:71], off offset:512
	s_nop 1
	v_lshlrev_b32_e32 v68, 16, v194
	v_and_b32_e32 v69, 0xffff0000, v194
	v_alignbit_b32 v70, v195, v194, 16
	v_and_b32_e32 v70, 0xffff0000, v70
	v_and_b32_e32 v71, 0xffff0000, v195
	v_pk_fma_f32 v[64:65], v[64:65], v[128:129], v[68:69]
	v_add_u32_e32 v68, 0x80, v160
	v_pk_fma_f32 v[66:67], v[66:67], v[130:131], v[70:71]
	v_ashrrev_i32_e32 v69, 31, v68
	global_store_dwordx4 v[80:81], v[64:67], off offset:576
	s_nop 1
	v_lshlrev_b64 v[68:69], 12, v[68:69]
	v_lshl_add_u64 v[68:69], s[50:51], 0, v[68:69]
	v_lshl_add_u64 v[68:69], v[68:69], 0, v[156:157]
	s_waitcnt vmcnt(31)
	v_lshlrev_b32_e32 v104, 16, v220
	v_and_b32_e32 v105, 0xffff0000, v220
	v_alignbit_b32 v220, v221, v220, 16
	v_and_b32_e32 v220, 0xffff0000, v220
	v_and_b32_e32 v221, 0xffff0000, v221
	v_pk_fma_f32 v[60:61], v[60:61], v[140:141], v[104:105]
	v_pk_fma_f32 v[62:63], v[62:63], v[142:143], v[220:221]
	global_store_dwordx4 v[68:69], v[60:63], off
	s_waitcnt vmcnt(31)
	s_nop 0
	v_alignbit_b32 v62, v223, v222, 16
	v_lshlrev_b32_e32 v60, 16, v222
	v_and_b32_e32 v61, 0xffff0000, v222
	v_and_b32_e32 v62, 0xffff0000, v62
	v_and_b32_e32 v63, 0xffff0000, v223
	v_pk_fma_f32 v[56:57], v[56:57], v[136:137], v[60:61]
	v_pk_fma_f32 v[58:59], v[58:59], v[138:139], v[62:63]
	global_store_dwordx4 v[68:69], v[56:59], off offset:64
	s_waitcnt vmcnt(31)
; __device__ __forceinline__ unsigned cvt_pk_bf16(float lo, float hi) { unsigned r; asm volatile("v_cvt_pk_bf16_f32 %0, %1, %2" : "=v"(r) : "v"(lo), "v"(hi)); return r; }
;     __device__ __forceinline__ void operator()(const f32x4 (&acc)[2][2][4][2], const Unit& u, int wr, int wc, int fr, int fq) const {
;     ...
;             for (int m = 0; m < 4; ++m) { const size_t off = (size_t)(row0 + ai * HALF + m * 16) * 1024 + col0;
; #pragma unroll
;                 for (int bj = 0; bj < 2; ++bj)
; #pragma unroll
;                     for (int n = 0; n < 2; ++n) {
;                         f32x4 b4;
;                         if (BASE_BF16) { const unsigned long long w = bw[m][bj][n];
;                             b4 = (f32x4){__uint_as_float((unsigned)(w & 0xffffull) << 16), __uint_as_float((unsigned)((w >> 16) & 0xffffull) << 16),
;                                          __uint_as_float((unsigned)((w >> 32) & 0xffffull) << 16), __uint_as_float((unsigned)((w >> 48) & 0xffffull) << 16)}; }
;                         else b4 = bv[m][bj][n];
;                         const f32x4 o = b4 + gv[bj][n] * acc[ai][bj][m][n];
;                         if (OUT_BF16) *(unsigned long long*)((bf16_t*)out + off + bj * HALF + 16 * n) = (unsigned long long)cvt_pk_bf16(o[0], o[1]) | ((unsigned long long)cvt_pk_bf16(o[2], o[3]) << 32);
;                         else *(f32x4*)((float*)out + off + bj * HALF + 16 * n) = o; } }
	s_nop 0
	v_alignbit_b32 v58, v225, v224, 16
	v_lshlrev_b32_e32 v56, 16, v224
	v_and_b32_e32 v57, 0xffff0000, v224
	v_and_b32_e32 v58, 0xffff0000, v58
	v_and_b32_e32 v59, 0xffff0000, v225
	v_pk_fma_f32 v[52:53], v[52:53], v[132:133], v[56:57]
	v_pk_fma_f32 v[54:55], v[54:55], v[134:135], v[58:59]
	global_store_dwordx4 v[68:69], v[52:55], off offset:512
	s_waitcnt vmcnt(31)
	s_nop 0
	v_alignbit_b32 v54, v227, v226, 16
	v_lshlrev_b32_e32 v52, 16, v226
	v_and_b32_e32 v53, 0xffff0000, v226
	v_and_b32_e32 v54, 0xffff0000, v54
	v_and_b32_e32 v55, 0xffff0000, v227
	v_pk_fma_f32 v[44:45], v[44:45], v[128:129], v[52:53]
	v_pk_fma_f32 v[46:47], v[46:47], v[130:131], v[54:55]
	global_store_dwordx4 v[68:69], v[44:47], off offset:576
	v_lshlrev_b64 v[52:53], 12, v[78:79]
	s_waitcnt vmcnt(31)
	v_lshlrev_b32_e32 v44, 16, v228
	v_and_b32_e32 v45, 0xffff0000, v228
	v_alignbit_b32 v46, v229, v228, 16
	v_and_b32_e32 v46, 0xffff0000, v46
	v_and_b32_e32 v47, 0xffff0000, v229
	v_pk_fma_f32 v[44:45], v[48:49], v[140:141], v[44:45]
	v_lshl_add_u64 v[48:49], s[50:51], 0, v[52:53]
	v_pk_fma_f32 v[46:47], v[50:51], v[142:143], v[46:47]
	v_lshl_add_u64 v[48:49], v[48:49], 0, v[156:157]
	global_store_dwordx4 v[48:49], v[44:47], off
	s_waitcnt vmcnt(31)
	s_nop 0
	v_alignbit_b32 v46, v231, v230, 16
	v_lshlrev_b32_e32 v44, 16, v230
	v_and_b32_e32 v45, 0xffff0000, v230
	v_and_b32_e32 v46, 0xffff0000, v46
	v_and_b32_e32 v47, 0xffff0000, v231
	v_pk_fma_f32 v[40:41], v[40:41], v[136:137], v[44:45]
	v_pk_fma_f32 v[42:43], v[42:43], v[138:139], v[46:47]
	global_store_dwordx4 v[48:49], v[40:43], off offset:64
	s_waitcnt vmcnt(31)
	s_nop 0
	v_alignbit_b32 v42, v233, v232, 16
	v_lshlrev_b32_e32 v40, 16, v232
	v_and_b32_e32 v41, 0xffff0000, v232
	v_and_b32_e32 v42, 0xffff0000, v42
	v_and_b32_e32 v43, 0xffff0000, v233
	v_pk_fma_f32 v[36:37], v[36:37], v[132:133], v[40:41]
	v_pk_fma_f32 v[38:39], v[38:39], v[134:135], v[42:43]
	global_store_dwordx4 v[48:49], v[36:39], off offset:512
	s_waitcnt vmcnt(31)
	s_nop 0
	v_alignbit_b32 v38, v235, v234, 16
	v_lshlrev_b32_e32 v36, 16, v234
	v_and_b32_e32 v37, 0xffff0000, v234
	v_and_b32_e32 v38, 0xffff0000, v38
	v_and_b32_e32 v39, 0xffff0000, v235
	v_pk_fma_f32 v[28:29], v[28:29], v[128:129], v[36:37]
	v_pk_fma_f32 v[30:31], v[30:31], v[130:131], v[38:39]
	global_store_dwordx4 v[48:49], v[28:31], off offset:576
	v_lshlrev_b64 v[36:37], 12, v[88:89]
	s_waitcnt vmcnt(31)
	v_lshlrev_b32_e32 v28, 16, v236
	v_and_b32_e32 v29, 0xffff0000, v236
	v_alignbit_b32 v30, v237, v236, 16
	v_and_b32_e32 v30, 0xffff0000, v30
	v_and_b32_e32 v31, 0xffff0000, v237
	v_pk_fma_f32 v[28:29], v[32:33], v[140:141], v[28:29]
	v_lshl_add_u64 v[32:33], s[50:51], 0, v[36:37]
	v_pk_fma_f32 v[30:31], v[34:35], v[142:143], v[30:31]
	v_lshl_add_u64 v[32:33], v[32:33], 0, v[156:157]
	global_store_dwordx4 v[32:33], v[28:31], off
	s_waitcnt vmcnt(31)
	s_nop 0
	v_alignbit_b32 v30, v239, v238, 16
	v_lshlrev_b32_e32 v28, 16, v238
	v_and_b32_e32 v29, 0xffff0000, v238
	v_and_b32_e32 v30, 0xffff0000, v30
	v_and_b32_e32 v31, 0xffff0000, v239
	v_pk_fma_f32 v[24:25], v[24:25], v[136:137], v[28:29]
	v_pk_fma_f32 v[26:27], v[26:27], v[138:139], v[30:31]
	global_store_dwordx4 v[32:33], v[24:27], off offset:64
	s_waitcnt vmcnt(31)
	s_nop 0
	v_alignbit_b32 v26, v241, v240, 16
	v_lshlrev_b32_e32 v24, 16, v240
	v_and_b32_e32 v25, 0xffff0000, v240
	v_and_b32_e32 v26, 0xffff0000, v26
	v_and_b32_e32 v27, 0xffff0000, v241
	v_pk_fma_f32 v[20:21], v[20:21], v[132:133], v[24:25]
	v_pk_fma_f32 v[22:23], v[22:23], v[134:135], v[26:27]
	global_store_dwordx4 v[32:33], v[20:23], off offset:512
	s_waitcnt vmcnt(31)
	s_nop 0
	v_alignbit_b32 v22, v243, v242, 16
	v_lshlrev_b32_e32 v20, 16, v242
	v_and_b32_e32 v21, 0xffff0000, v242
	v_and_b32_e32 v22, 0xffff0000, v22
	v_and_b32_e32 v23, 0xffff0000, v243
	v_pk_fma_f32 v[12:13], v[12:13], v[128:129], v[20:21]
	v_pk_fma_f32 v[14:15], v[14:15], v[130:131], v[22:23]
	global_store_dwordx4 v[32:33], v[12:15], off offset:576
	v_lshlrev_b64 v[20:21], 12, v[98:99]
	s_waitcnt vmcnt(31)
	v_lshlrev_b32_e32 v12, 16, v244
	v_and_b32_e32 v13, 0xffff0000, v244
	v_alignbit_b32 v14, v245, v244, 16
	v_and_b32_e32 v14, 0xffff0000, v14
	v_and_b32_e32 v15, 0xffff0000, v245
	v_pk_fma_f32 v[12:13], v[16:17], v[140:141], v[12:13]
	v_lshl_add_u64 v[16:17], s[50:51], 0, v[20:21]
	v_pk_fma_f32 v[14:15], v[18:19], v[142:143], v[14:15]
	v_lshl_add_u64 v[16:17], v[16:17], 0, v[156:157]
	global_store_dwordx4 v[16:17], v[12:15], off
	s_waitcnt vmcnt(31)
	s_nop 0
	v_alignbit_b32 v14, v247, v246, 16
	v_lshlrev_b32_e32 v12, 16, v246
	v_and_b32_e32 v13, 0xffff0000, v246
	v_and_b32_e32 v14, 0xffff0000, v14
	v_and_b32_e32 v15, 0xffff0000, v247
	v_pk_fma_f32 v[8:9], v[8:9], v[136:137], v[12:13]
	v_pk_fma_f32 v[10:11], v[10:11], v[138:139], v[14:15]
	global_store_dwordx4 v[16:17], v[8:11], off offset:64
	s_waitcnt vmcnt(31)
	s_nop 0
	v_alignbit_b32 v10, v251, v250, 16
	v_lshlrev_b32_e32 v8, 16, v250
	v_and_b32_e32 v9, 0xffff0000, v250
	v_and_b32_e32 v10, 0xffff0000, v10
	v_and_b32_e32 v11, 0xffff0000, v251
	v_pk_fma_f32 v[4:5], v[4:5], v[132:133], v[8:9]
	v_pk_fma_f32 v[6:7], v[6:7], v[134:135], v[10:11]
	global_store_dwordx4 v[16:17], v[4:7], off offset:512
	s_waitcnt vmcnt(31)
	s_nop 0
	v_alignbit_b32 v6, v249, v248, 16
	v_lshlrev_b32_e32 v4, 16, v248
	v_and_b32_e32 v5, 0xffff0000, v248
	v_and_b32_e32 v6, 0xffff0000, v6
	v_and_b32_e32 v7, 0xffff0000, v249
	v_pk_fma_f32 v[0:1], v[0:1], v[128:129], v[4:5]
	v_pk_fma_f32 v[2:3], v[2:3], v[130:131], v[6:7]
	global_store_dwordx4 v[16:17], v[0:3], off offset:576
	s_cbranch_vccnz .LBB0_1468
	s_andn2_b64 vcc, exec, s[6:7]
	s_cbranch_vccnz .LBB0_1467
	s_barrier
	s_branch .LBB0_1467
